# P1 and merged-GEMM K-loops in double phases, VGPR-address DMA (second sitting)
# speedup vs baseline: 1.0013x; 1.0013x over previous
.LBB0_181:
	ds_read_b128 v[144:147], v157
	ds_read_b128 v[148:151], v157 offset:1024
	ds_read_b128 v[162:165], v157 offset:2048
	ds_read_b128 v[166:169], v157 offset:3072
	s_add_u32 s30, s28, 0xfff80080
	s_addc_u32 s31, s29, -1
	s_cmp_eq_u32 s54, 28
	s_cselect_b32 s35, s2, s31
	s_cselect_b32 s34, s3, s30
	s_cselect_b32 s31, s7, s27
	s_cselect_b32 s30, s9, s11
	v_lshl_add_u64 v[152:153], s[28:29], 0, v[136:137]
	s_add_i32 m0, s39, 0xc000
	ds_read_b128 v[170:173], v158
	ds_read_b128 v[174:177], v158 offset:1024
	ds_read_b128 v[178:181], v158 offset:2048
	ds_read_b128 v[186:189], v158 offset:3072
	ds_read_b128 v[194:197], v158 offset:4096
	ds_read_b128 v[198:201], v158 offset:5120
	ds_read_b128 v[202:205], v158 offset:6144
	ds_read_b128 v[206:209], v158 offset:7168
	global_load_lds_dwordx4 v[152:153], off
	v_lshl_add_u64 v[152:153], s[28:29], 0, v[138:139]
	s_add_i32 m0, s39, 0xe000
	s_nop 0
	global_load_lds_dwordx4 v[152:153], off
	ds_read_b128 v[210:213], v159
	ds_read_b128 v[214:217], v159 offset:1024
	ds_read_b128 v[218:221], v159 offset:2048
	ds_read_b128 v[222:225], v159 offset:3072
	s_waitcnt lgkmcnt(0)
	s_barrier
	s_setprio 1
	v_mfma_f32_16x16x32_bf16 v[124:127], v[144:147], v[170:173], v[124:127]
	v_mfma_f32_16x16x32_bf16 v[120:123], v[162:165], v[170:173], v[120:123]
	v_mfma_f32_16x16x32_bf16 v[108:111], v[144:147], v[178:181], v[108:111]
	v_mfma_f32_16x16x32_bf16 v[104:107], v[162:165], v[178:181], v[104:107]
	v_mfma_f32_16x16x32_bf16 v[92:95], v[144:147], v[194:197], v[92:95]
	v_mfma_f32_16x16x32_bf16 v[88:91], v[162:165], v[194:197], v[88:91]
	v_mfma_f32_16x16x32_bf16 v[76:79], v[144:147], v[202:205], v[76:79]
	v_mfma_f32_16x16x32_bf16 v[72:75], v[162:165], v[202:205], v[72:75]
	v_mfma_f32_16x16x32_bf16 v[124:127], v[148:151], v[174:177], v[124:127]
	v_mfma_f32_16x16x32_bf16 v[120:123], v[166:169], v[174:177], v[120:123]
	v_mfma_f32_16x16x32_bf16 v[108:111], v[148:151], v[186:189], v[108:111]
	v_mfma_f32_16x16x32_bf16 v[104:107], v[166:169], v[186:189], v[104:107]
	v_mfma_f32_16x16x32_bf16 v[92:95], v[148:151], v[198:201], v[92:95]
	v_mfma_f32_16x16x32_bf16 v[88:91], v[166:169], v[198:201], v[88:91]
	v_mfma_f32_16x16x32_bf16 v[76:79], v[148:151], v[206:209], v[76:79]
	v_mfma_f32_16x16x32_bf16 v[72:75], v[166:169], v[206:209], v[72:75]
	v_mfma_f32_16x16x32_bf16 v[116:119], v[210:213], v[170:173], v[116:119]
	v_mfma_f32_16x16x32_bf16 v[112:115], v[218:221], v[170:173], v[112:115]
	v_mfma_f32_16x16x32_bf16 v[100:103], v[210:213], v[178:181], v[100:103]
	v_mfma_f32_16x16x32_bf16 v[96:99], v[218:221], v[178:181], v[96:99]
	v_mfma_f32_16x16x32_bf16 v[84:87], v[210:213], v[194:197], v[84:87]
	v_mfma_f32_16x16x32_bf16 v[80:83], v[218:221], v[194:197], v[80:83]
	v_mfma_f32_16x16x32_bf16 v[68:71], v[210:213], v[202:205], v[68:71]
	v_mfma_f32_16x16x32_bf16 v[64:67], v[218:221], v[202:205], v[64:67]
	v_mfma_f32_16x16x32_bf16 v[116:119], v[214:217], v[174:177], v[116:119]
	v_mfma_f32_16x16x32_bf16 v[112:115], v[222:225], v[174:177], v[112:115]
	v_mfma_f32_16x16x32_bf16 v[100:103], v[214:217], v[186:189], v[100:103]
	v_mfma_f32_16x16x32_bf16 v[96:99], v[222:225], v[186:189], v[96:99]
	v_mfma_f32_16x16x32_bf16 v[84:87], v[214:217], v[198:201], v[84:87]
	v_mfma_f32_16x16x32_bf16 v[80:83], v[222:225], v[198:201], v[80:83]
	v_mfma_f32_16x16x32_bf16 v[68:71], v[214:217], v[206:209], v[68:71]
	v_mfma_f32_16x16x32_bf16 v[64:67], v[222:225], v[206:209], v[64:67]
	s_setprio 0
	s_barrier
	s_add_i32 s55, s48, s38
	v_lshl_add_u64 v[152:153], s[30:31], 0, v[130:131]
	s_mov_b32 m0, s55
	s_nop 0
	global_load_lds_dwordx4 v[152:153], off
	v_lshl_add_u64 v[182:183], s[30:31], 0, v[134:135]
	s_add_i32 m0, s55, 0x2000
	s_nop 0
	global_load_lds_dwordx4 v[182:183], off
	s_mov_b32 m0, s39
	v_lshl_add_u64 v[190:191], s[34:35], 0, v[128:129]
	ds_read_b128 v[170:173], v158 offset:16384
	ds_read_b128 v[174:177], v158 offset:17408
	ds_read_b128 v[178:181], v158 offset:18432
	ds_read_b128 v[186:189], v158 offset:19456
	ds_read_b128 v[194:197], v158 offset:20480
	ds_read_b128 v[198:201], v158 offset:21504
	ds_read_b128 v[202:205], v158 offset:22528
	ds_read_b128 v[206:209], v158 offset:23552
	global_load_lds_dwordx4 v[190:191], off
	v_lshl_add_u64 v[226:227], s[34:35], 0, v[132:133]
	s_mov_b32 m0, s40
	s_nop 0
	global_load_lds_dwordx4 v[226:227], off
	s_add_u32 s56, s30, 0x80000
	s_addc_u32 s57, s31, 0
	s_add_i32 s55, s49, s38
	v_lshl_add_u64 v[246:247], s[56:57], 0, v[130:131]
	s_mov_b32 m0, s55
	s_nop 0
	global_load_lds_dwordx4 v[246:247], off
	v_lshl_add_u64 v[248:249], s[56:57], 0, v[134:135]
	s_add_i32 m0, s55, 0x2000
	s_nop 0
	global_load_lds_dwordx4 v[248:249], off
	s_waitcnt vmcnt(6)
	s_waitcnt lgkmcnt(0)
	s_barrier
	s_setprio 1
	v_mfma_f32_16x16x32_bf16 v[60:63], v[144:147], v[170:173], v[60:63]
	v_mfma_f32_16x16x32_bf16 v[56:59], v[162:165], v[170:173], v[56:59]
	v_mfma_f32_16x16x32_bf16 v[44:47], v[144:147], v[178:181], v[44:47]
	v_mfma_f32_16x16x32_bf16 v[40:43], v[162:165], v[178:181], v[40:43]
	v_mfma_f32_16x16x32_bf16 v[28:31], v[144:147], v[194:197], v[28:31]
	v_mfma_f32_16x16x32_bf16 v[24:27], v[162:165], v[194:197], v[24:27]
	v_mfma_f32_16x16x32_bf16 v[12:15], v[144:147], v[202:205], v[12:15]
	v_mfma_f32_16x16x32_bf16 v[8:11], v[162:165], v[202:205], v[8:11]
	v_mfma_f32_16x16x32_bf16 v[60:63], v[148:151], v[174:177], v[60:63]
	v_mfma_f32_16x16x32_bf16 v[56:59], v[166:169], v[174:177], v[56:59]
	v_mfma_f32_16x16x32_bf16 v[44:47], v[148:151], v[186:189], v[44:47]
	v_mfma_f32_16x16x32_bf16 v[40:43], v[166:169], v[186:189], v[40:43]
	v_mfma_f32_16x16x32_bf16 v[28:31], v[148:151], v[198:201], v[28:31]
	v_mfma_f32_16x16x32_bf16 v[24:27], v[166:169], v[198:201], v[24:27]
	v_mfma_f32_16x16x32_bf16 v[12:15], v[148:151], v[206:209], v[12:15]
	v_mfma_f32_16x16x32_bf16 v[8:11], v[166:169], v[206:209], v[8:11]
	v_mfma_f32_16x16x32_bf16 v[52:55], v[210:213], v[170:173], v[52:55]
	v_mfma_f32_16x16x32_bf16 v[48:51], v[218:221], v[170:173], v[48:51]
	v_mfma_f32_16x16x32_bf16 v[36:39], v[210:213], v[178:181], v[36:39]
	v_mfma_f32_16x16x32_bf16 v[32:35], v[218:221], v[178:181], v[32:35]
	v_mfma_f32_16x16x32_bf16 v[20:23], v[210:213], v[194:197], v[20:23]
	v_mfma_f32_16x16x32_bf16 v[16:19], v[218:221], v[194:197], v[16:19]
	v_mfma_f32_16x16x32_bf16 v[4:7], v[210:213], v[202:205], v[4:7]
	v_mfma_f32_16x16x32_bf16 v[0:3], v[218:221], v[202:205], v[0:3]
	v_mfma_f32_16x16x32_bf16 v[52:55], v[214:217], v[174:177], v[52:55]
	v_mfma_f32_16x16x32_bf16 v[48:51], v[222:225], v[174:177], v[48:51]
	v_mfma_f32_16x16x32_bf16 v[36:39], v[214:217], v[186:189], v[36:39]
	v_mfma_f32_16x16x32_bf16 v[32:35], v[222:225], v[186:189], v[32:35]
	v_mfma_f32_16x16x32_bf16 v[20:23], v[214:217], v[198:201], v[20:23]
	v_mfma_f32_16x16x32_bf16 v[16:19], v[222:225], v[198:201], v[16:19]
	v_mfma_f32_16x16x32_bf16 v[4:7], v[214:217], v[206:209], v[4:7]
	v_mfma_f32_16x16x32_bf16 v[0:3], v[222:225], v[206:209], v[0:3]
	s_setprio 0
	s_add_i32 s55, 0, 0x18000
	v_add_u32_e32 v161, s55, v155
	s_barrier
	ds_read_b128 v[144:147], v161
	ds_read_b128 v[148:151], v161 offset:1024
	ds_read_b128 v[162:165], v161 offset:2048
	ds_read_b128 v[166:169], v161 offset:3072
	s_add_u32 s34, s34, 0x80000
	s_addc_u32 s35, s35, 0
	s_mov_b32 m0, s41
	v_lshl_add_u64 v[250:251], s[34:35], 0, v[128:129]
	ds_read_b128 v[170:173], v158 offset:32768
	ds_read_b128 v[174:177], v158 offset:33792
	ds_read_b128 v[178:181], v158 offset:34816
	ds_read_b128 v[186:189], v158 offset:35840
	ds_read_b128 v[194:197], v158 offset:36864
	ds_read_b128 v[198:201], v158 offset:37888
	ds_read_b128 v[202:205], v158 offset:38912
	ds_read_b128 v[206:209], v158 offset:39936
	global_load_lds_dwordx4 v[250:251], off
	v_lshl_add_u64 v[252:253], s[34:35], 0, v[132:133]
	s_mov_b32 m0, s42
	s_nop 0
	global_load_lds_dwordx4 v[252:253], off
	v_add_u32_e32 v161, 0x1c000, v155
	ds_read_b128 v[210:213], v161
	ds_read_b128 v[214:217], v161 offset:1024
	ds_read_b128 v[218:221], v161 offset:2048
	ds_read_b128 v[222:225], v161 offset:3072
	s_waitcnt lgkmcnt(0)
	s_barrier
	s_setprio 1
	v_mfma_f32_16x16x32_bf16 v[124:127], v[144:147], v[170:173], v[124:127]
	v_mfma_f32_16x16x32_bf16 v[120:123], v[162:165], v[170:173], v[120:123]
	v_mfma_f32_16x16x32_bf16 v[108:111], v[144:147], v[178:181], v[108:111]
	v_mfma_f32_16x16x32_bf16 v[104:107], v[162:165], v[178:181], v[104:107]
	v_mfma_f32_16x16x32_bf16 v[92:95], v[144:147], v[194:197], v[92:95]
	v_mfma_f32_16x16x32_bf16 v[88:91], v[162:165], v[194:197], v[88:91]
	v_mfma_f32_16x16x32_bf16 v[76:79], v[144:147], v[202:205], v[76:79]
	v_mfma_f32_16x16x32_bf16 v[72:75], v[162:165], v[202:205], v[72:75]
	v_mfma_f32_16x16x32_bf16 v[124:127], v[148:151], v[174:177], v[124:127]
	v_mfma_f32_16x16x32_bf16 v[120:123], v[166:169], v[174:177], v[120:123]
	v_mfma_f32_16x16x32_bf16 v[108:111], v[148:151], v[186:189], v[108:111]
	v_mfma_f32_16x16x32_bf16 v[104:107], v[166:169], v[186:189], v[104:107]
	v_mfma_f32_16x16x32_bf16 v[92:95], v[148:151], v[198:201], v[92:95]
	v_mfma_f32_16x16x32_bf16 v[88:91], v[166:169], v[198:201], v[88:91]
	v_mfma_f32_16x16x32_bf16 v[76:79], v[148:151], v[206:209], v[76:79]
	v_mfma_f32_16x16x32_bf16 v[72:75], v[166:169], v[206:209], v[72:75]
	v_mfma_f32_16x16x32_bf16 v[116:119], v[210:213], v[170:173], v[116:119]
	v_mfma_f32_16x16x32_bf16 v[112:115], v[218:221], v[170:173], v[112:115]
	v_mfma_f32_16x16x32_bf16 v[100:103], v[210:213], v[178:181], v[100:103]
	v_mfma_f32_16x16x32_bf16 v[96:99], v[218:221], v[178:181], v[96:99]
	v_mfma_f32_16x16x32_bf16 v[84:87], v[210:213], v[194:197], v[84:87]
	v_mfma_f32_16x16x32_bf16 v[80:83], v[218:221], v[194:197], v[80:83]
	v_mfma_f32_16x16x32_bf16 v[68:71], v[210:213], v[202:205], v[68:71]
	v_mfma_f32_16x16x32_bf16 v[64:67], v[218:221], v[202:205], v[64:67]
	v_mfma_f32_16x16x32_bf16 v[116:119], v[214:217], v[174:177], v[116:119]
	v_mfma_f32_16x16x32_bf16 v[112:115], v[222:225], v[174:177], v[112:115]
	v_mfma_f32_16x16x32_bf16 v[100:103], v[214:217], v[186:189], v[100:103]
	v_mfma_f32_16x16x32_bf16 v[96:99], v[222:225], v[186:189], v[96:99]
	v_mfma_f32_16x16x32_bf16 v[84:87], v[214:217], v[198:201], v[84:87]
	v_mfma_f32_16x16x32_bf16 v[80:83], v[222:225], v[198:201], v[80:83]
	v_mfma_f32_16x16x32_bf16 v[68:71], v[214:217], v[206:209], v[68:71]
	v_mfma_f32_16x16x32_bf16 v[64:67], v[222:225], v[206:209], v[64:67]
	s_setprio 0
	s_barrier
; __device__ __forceinline__ unsigned pk2(float lo, float hi) { unsigned r; asm("v_cvt_pk_bf16_f32 %0, %1, %2" : "=v"(r) : "v"(lo), "v"(hi)); return r; }
; template <class Epi>
; __device__ __forceinline__ void gemm_phase(LAS unsigned char* lds, const GemmD g, const Epi& E) {
;     ...
;         for (int t = 0; t < nt; t += 2) PG8_KITER(t);
;     __device__ __forceinline__ void operator()(const f32x4 (&acc)[2][2][4][2], const Unit& u, int wr, int wc, int fr, int fq) const {
;         const int row0 = u.pm * BM + wr * 64 + fr, col0 = u.pn * BM + wc * 32 + 8 * fq;
;         const bool sig = (u.pn >= 36 && u.pn < 52), isdt = (u.pn == 52);
; #pragma unroll
;         for (int ai = 0; ai < 2; ++ai)
; #pragma unroll
;             for (int m = 0; m < 4; ++m) { const int row = row0 + ai * HALF + m * 16;
; #pragma unroll
;                 for (int bj = 0; bj < 2; ++bj) { const f32x4 v0 = acc[ai][bj][m][0], v1 = acc[ai][bj][m][1]; const int col = col0 + bj * HALF;
;                     if (sig) {
;                         const int c = (col - C_GS) >> 1;
;                         float ra[4], gp[4];
; #pragma unroll
;                         for (int j = 0; j < 4; ++j) { const float ea = __expf(-fminf(fmaxf(v0[j], -30.f), 30.f)), eb = __expf(-fminf(fmaxf(v1[j], -30.f), 30.f)); gp[j] = __builtin_amdgcn_rcpf(1.0f + eb); ra[j] = (1.0f + eb) * __builtin_amdgcn_rcpf(1.0f + ea); }
;                         u32x2 wr_, wg; wr_.x = pk2(ra[0], ra[1]); wr_.y = pk2(ra[2], ra[3]); wg.x = pk2(gp[0], gp[1]); wg.y = pk2(gp[2], gp[3]);
;                         *(u32x2*)(proj + (size_t)row * NPROJ + C_GS + c) = wr_;
;                         *(u32x2*)(proj + (size_t)row * NPROJ + C_GP + c) = wg;
;                     } else {
;                         u32x4 w; w.x = pk2(v0[0], v0[1]); w.y = pk2(v0[2], v0[3]); w.z = pk2(v1[0], v1[1]); w.w = pk2(v1[2], v1[3]);
;                         *(u32x4*)(proj + (size_t)row * NPROJ + col) = w;
;                         if (isdt && col < C_DT + 32) { float* d = dtraw + (size_t)row * 32 + (col - C_DT); *(f32x4*)d = v0; *(f32x4*)(d + 4) = v1; } } } }
	s_add_i32 s34, 0, 0x1c000
	s_add_i32 s35, s55, s38
	v_lshl_add_u64 v[152:153], v[152:153], 0, s[0:1]
	s_mov_b32 m0, s35
	s_nop 0
	global_load_lds_dwordx4 v[152:153], off
	v_lshl_add_u64 v[152:153], v[182:183], 0, s[0:1]
	s_add_i32 m0, s35, 0x2000
	s_nop 0
	global_load_lds_dwordx4 v[152:153], off
	s_mov_b32 m0, s44
	v_lshl_add_u64 v[152:153], v[190:191], 0, s[0:1]
	ds_read_b128 v[170:173], v158 offset:49152
	ds_read_b128 v[174:177], v158 offset:50176
	ds_read_b128 v[178:181], v158 offset:51200
	ds_read_b128 v[186:189], v158 offset:52224
	ds_read_b128 v[194:197], v158 offset:53248
	ds_read_b128 v[198:201], v158 offset:54272
	ds_read_b128 v[202:205], v158 offset:55296
	ds_read_b128 v[206:209], v158 offset:56320
	global_load_lds_dwordx4 v[152:153], off
	v_lshl_add_u64 v[152:153], v[226:227], 0, s[0:1]
	s_mov_b32 m0, s45
	s_nop 0
	global_load_lds_dwordx4 v[152:153], off
	s_add_u32 s30, s30, 0x80080
	s_addc_u32 s31, s31, 0
	s_add_i32 s34, s34, s38
	v_lshl_add_u64 v[246:247], s[30:31], 0, v[130:131]
	s_mov_b32 m0, s34
	s_nop 0
	global_load_lds_dwordx4 v[246:247], off
	v_lshl_add_u64 v[248:249], s[30:31], 0, v[134:135]
	s_add_i32 m0, s34, 0x2000
	s_nop 0
	global_load_lds_dwordx4 v[248:249], off
	s_waitcnt vmcnt(6)
	s_waitcnt lgkmcnt(0)
	s_barrier
	s_setprio 1
	v_mfma_f32_16x16x32_bf16 v[60:63], v[144:147], v[170:173], v[60:63]
	v_mfma_f32_16x16x32_bf16 v[56:59], v[162:165], v[170:173], v[56:59]
	v_mfma_f32_16x16x32_bf16 v[44:47], v[144:147], v[178:181], v[44:47]
	v_mfma_f32_16x16x32_bf16 v[40:43], v[162:165], v[178:181], v[40:43]
	v_mfma_f32_16x16x32_bf16 v[28:31], v[144:147], v[194:197], v[28:31]
	v_mfma_f32_16x16x32_bf16 v[24:27], v[162:165], v[194:197], v[24:27]
	v_mfma_f32_16x16x32_bf16 v[12:15], v[144:147], v[202:205], v[12:15]
	v_mfma_f32_16x16x32_bf16 v[8:11], v[162:165], v[202:205], v[8:11]
	v_mfma_f32_16x16x32_bf16 v[60:63], v[148:151], v[174:177], v[60:63]
	v_mfma_f32_16x16x32_bf16 v[56:59], v[166:169], v[174:177], v[56:59]
	v_mfma_f32_16x16x32_bf16 v[44:47], v[148:151], v[186:189], v[44:47]
	v_mfma_f32_16x16x32_bf16 v[40:43], v[166:169], v[186:189], v[40:43]
	v_mfma_f32_16x16x32_bf16 v[28:31], v[148:151], v[198:201], v[28:31]
	v_mfma_f32_16x16x32_bf16 v[24:27], v[166:169], v[198:201], v[24:27]
	v_mfma_f32_16x16x32_bf16 v[12:15], v[148:151], v[206:209], v[12:15]
	v_mfma_f32_16x16x32_bf16 v[8:11], v[166:169], v[206:209], v[8:11]
	v_mfma_f32_16x16x32_bf16 v[52:55], v[210:213], v[170:173], v[52:55]
	v_mfma_f32_16x16x32_bf16 v[48:51], v[218:221], v[170:173], v[48:51]
	v_mfma_f32_16x16x32_bf16 v[36:39], v[210:213], v[178:181], v[36:39]
	v_mfma_f32_16x16x32_bf16 v[32:35], v[218:221], v[178:181], v[32:35]
	v_mfma_f32_16x16x32_bf16 v[20:23], v[210:213], v[194:197], v[20:23]
	v_mfma_f32_16x16x32_bf16 v[16:19], v[218:221], v[194:197], v[16:19]
	v_mfma_f32_16x16x32_bf16 v[4:7], v[210:213], v[202:205], v[4:7]
	v_mfma_f32_16x16x32_bf16 v[0:3], v[218:221], v[202:205], v[0:3]
	v_mfma_f32_16x16x32_bf16 v[52:55], v[214:217], v[174:177], v[52:55]
	v_mfma_f32_16x16x32_bf16 v[48:51], v[222:225], v[174:177], v[48:51]
	v_mfma_f32_16x16x32_bf16 v[36:39], v[214:217], v[186:189], v[36:39]
	v_mfma_f32_16x16x32_bf16 v[32:35], v[222:225], v[186:189], v[32:35]
	v_mfma_f32_16x16x32_bf16 v[20:23], v[214:217], v[198:201], v[20:23]
	v_mfma_f32_16x16x32_bf16 v[16:19], v[222:225], v[198:201], v[16:19]
	v_mfma_f32_16x16x32_bf16 v[4:7], v[214:217], v[206:209], v[4:7]
	v_mfma_f32_16x16x32_bf16 v[0:3], v[222:225], v[206:209], v[0:3]
	s_setprio 0
	s_add_i32 s54, s54, 2
	s_add_u32 s28, s28, 0x100
	s_addc_u32 s29, s29, 0
	s_add_u32 s11, s11, 0x100
	s_addc_u32 s27, s27, 0
	s_cmp_gt_u32 s54, 29
	s_barrier
	s_cbranch_scc0 .LBB0_181
	s_sub_i32 s2, s6, 36
	v_lshl_add_u32 v146, s26, 8, v154
	s_cmp_gt_u32 s2, 15
	s_cselect_b64 s[28:29], -1, 0
	s_cmp_eq_u32 s6, 52
	v_ashrrev_i32_e32 v147, 31, v146
	v_mad_i64_i32 v[152:153], s[2:3], v146, s50, 0
	v_lshl_or_b32 v144, s6, 8, v156
	s_cselect_b64 s[26:27], -1, 0
	v_lshlrev_b64 v[150:151], 7, v[146:147]
	s_mov_b64 s[2:3], -1
	s_and_b64 vcc, exec, s[28:29]
	s_cbranch_vccz .LBB0_186
	v_lshl_add_u64 v[148:149], s[92:93], 0, v[152:153]
	v_ashrrev_i32_e32 v145, 31, v144
	v_cmp_gt_i32_e32 vcc, s52, v144
	v_lshl_add_u64 v[148:149], v[144:145], 1, v[148:149]
	s_and_b64 s[2:3], s[26:27], vcc
	v_cvt_pk_bf16_f32 v162, v124, v125
	v_cvt_pk_bf16_f32 v163, v126, v127
	v_cvt_pk_bf16_f32 v164, v120, v121
	v_cvt_pk_bf16_f32 v165, v122, v123
	global_store_dwordx4 v[148:149], v[162:165], off
	s_and_saveexec_b64 s[6:7], s[2:3]
	s_cbranch_execz .LBB0_185
	v_lshl_add_u64 v[148:149], s[14:15], 0, v[150:151]
	v_lshl_add_u64 v[148:149], v[144:145], 2, v[148:149]
	v_add_co_u32_e32 v162, vcc, 0xffff3000, v148
	s_nop 1
	v_addc_co_u32_e32 v163, vcc, -1, v149, vcc
	v_add_co_u32_e32 v148, vcc, 0xffff4000, v148
	global_store_dwordx4 v[162:163], v[124:127], off
	s_nop 0
	v_addc_co_u32_e32 v149, vcc, -1, v149, vcc
	global_store_dwordx4 v[148:149], v[120:123], off offset:-4080

; __device__ __forceinline__ const char* unit_a(const GemmD& g, const Unit& u) { return (const char*)(g.A + (size_t)u.pm * BM * g.lda + (g.a_kdiv ? (u.pn / g.a_kdiv) * g.a_kstride : 0) + u.sub * g.K); }
; __device__ __forceinline__ const char* unit_b(const GemmD& g, const Unit& u) { return (const char*)(g.Bt + (size_t)u.pn * BM * g.ldb + u.sub * g.K); }
; #define PG8_STAGE(bufoff, gbase, voff) do { _Pragma("unroll") for (int _i = 0; _i < 2; ++_i) \
;         __builtin_amdgcn_global_load_lds((const unsigned*)((const char*)(gbase) + (voff)[_i]), (LAS unsigned*)(lds + (bufoff) + ldsw + _i * 8192), 16, 0, 0); } while (0)
; #define PG8_WAIT_V(n) asm volatile("s_waitcnt vmcnt(" #n ")" ::: "memory")
; #define PG8_BAR __builtin_amdgcn_s_barrier()
; template <class Epi>
; __device__ __forceinline__ void gemm_phase(LAS unsigned char* lds, const GemmD g, const Epi& E) {
;     ...
;     for (int i = 0; i < 2; ++i) { int R, C; stage_rc(tid * 16 + i * 8192, R, C); const int Rb = (R & ~31) + perm32(R & 31);
;         voffA[i] = (unsigned)(R * g.lda + C) * 2u; voffB[i] = (unsigned)(Rb * g.ldb + C) * 2u; }
;     const size_t kstep = (size_t)(BK * 2);
;     const size_t hstepA = (size_t)HALF * g.lda * 2, hstepB = (size_t)HALF * g.ldb * 2;
;     const unsigned ldsw = (unsigned)wid * 1024u;
;     const int aoff = lds_byte(wr * 64 + fr, fq * 8), boff = lds_byte(wc * 32 + fr, fq * 8);
;     ...
;     Unit cur, nxt; int ui = 0;
;     if (!unit_next(g, 0, cur)) return;
;     f32x4 acc[2][2][4][2];
; #pragma unroll
;     for (int a = 0; a < 2; ++a)
; #pragma unroll
;         for (int b = 0; b < 2; ++b)
; #pragma unroll
;             for (int m = 0; m < 4; ++m)
; #pragma unroll
;                 for (int n = 0; n < 2; ++n) acc[a][b][m][n] = (f32x4){0.f, 0.f, 0.f, 0.f};
;     bf16x8 At[4][2], B0[2][2], B1[2][2];
;     const char* cA = unit_a(g, cur); const char* cB = unit_b(g, cur);
;     PG8_STAGE(PG8_SB(0, 0), cB, voffB); PG8_STAGE(PG8_SA(0, 0), cA, voffA); PG8_STAGE(PG8_SB(0, 1), cB + hstepB, voffB); PG8_STAGE(PG8_SA(0, 1), cA + hstepA, voffA);
;     if (wr == 1) PG8_BAR;
;     PG8_WAIT_V(4); PG8_BAR;
;     PG8_STAGE(PG8_SB(1, 0), cB + kstep, voffB); PG8_STAGE(PG8_SA(1, 0), cA + kstep, voffA); PG8_STAGE(PG8_SB(1, 1), cB + hstepB + kstep, voffB);
;     PG8_WAIT_V(6); PG8_BAR;
.LBB0_889:
	v_readlane_b32 s24, v242, 11
	v_mov_b32_e32 v185, v1
	v_readlane_b32 s25, v242, 12
	v_mov_b32_e32 v181, v1
	v_readlane_b32 s30, v242, 7
	v_lshl_add_u64 v[8:9], s[24:25], 0, v[184:185]
	v_lshl_add_u64 v[10:11], s[24:25], 0, v[180:181]
	v_mov_b32_e32 v187, v1
	v_readlane_b32 s31, v242, 8
	s_add_i32 m0, s46, 0x18000
	v_lshl_add_u64 v[8:9], v[8:9], 0, s[48:49]
	s_waitcnt vmcnt(0)
	v_lshl_add_u64 v[12:13], s[30:31], 0, v[186:187]
	v_mov_b32_e32 v183, v1
	s_waitcnt vmcnt(0)
	s_barrier
	global_load_lds_dwordx4 v[8:9], off
	v_lshl_add_u64 v[8:9], v[10:11], 0, s[48:49]
	s_add_i32 m0, s46, 0x1a000
	s_add_i32 s56, s46, 0x8000
	v_lshl_add_u64 v[14:15], s[30:31], 0, v[182:183]
	global_load_lds_dwordx4 v[8:9], off
	v_lshl_add_u64 v[8:9], v[12:13], 0, s[48:49]
	s_mov_b32 m0, s56
	s_add_i32 s57, s46, 0xa000
	v_readlane_b32 s2, v242, 13
	global_load_lds_dwordx4 v[8:9], off
	v_lshl_add_u64 v[8:9], v[14:15], 0, s[48:49]
	s_mov_b32 m0, s57
	v_readlane_b32 s3, v242, 14
	global_load_lds_dwordx4 v[8:9], off
	s_add_i32 m0, s46, 0x1c000
	v_lshl_add_u64 v[8:9], s[2:3], 0, v[184:185]
	global_load_lds_dwordx4 v[8:9], off
	v_lshl_add_u64 v[8:9], s[2:3], 0, v[180:181]
	s_add_i32 m0, s46, 0x1e000
	s_lshl_b32 s0, s0, 5
	global_load_lds_dwordx4 v[8:9], off
	v_lshrrev_b32_e32 v9, 1, v2
	v_and_b32_e32 v9, 24, v9
	v_and_b32_e32 v8, 15, v2
	v_lshlrev_b32_e32 v10, 1, v9
	v_lshlrev_b32_e32 v2, 2, v2
	v_lshl_or_b32 v203, s1, 6, v8
	v_lshl_or_b32 v8, v8, 6, v10
	s_lshl_b32 s1, s1, 13
	v_and_b32_e32 v2, 32, v2
	s_and_b32 s0, s0, 0x60
	v_bitop3_b32 v10, v8, s1, v2 bitop3:0xde
	s_lshl_b32 s1, s0, 7
	v_bitop3_b32 v204, v8, s1, v2 bitop3:0xde
	v_lshlrev_b32_e32 v2, 16, v6
	v_and_b32_e32 v2, 0xfffe0000, v2
	v_lshl_add_u32 v2, v5, 13, v2
	v_and_b32_e32 v5, 1, v6
	v_lshl_or_b32 v2, v5, 6, v2
	v_lshl_add_u32 v188, v7, 1, v2
	v_lshlrev_b32_e32 v2, 16, v0
	v_and_b32_e32 v2, 0xfffe0000, v2
	v_or_b32_e32 v205, s0, v9
	v_lshl_add_u32 v2, v3, 13, v2
	v_and_b32_e32 v0, 1, v0
	v_readlane_b32 s0, v242, 2
	s_waitcnt vmcnt(6)
	v_lshl_or_b32 v0, v0, 6, v2
	v_mov_b32_e32 v2, v1
	v_mov_b32_e32 v3, v1
	v_readlane_b32 s1, v242, 3
	v_lshl_add_u32 v190, v4, 1, v0
	v_mov_b32_e32 v0, v1
	v_add_u32_e32 v206, 0, v10
	v_mov_b64_e32 v[130:131], v[2:3]
	v_mov_b64_e32 v[126:127], v[2:3]
	v_mov_b64_e32 v[122:123], v[2:3]
	v_mov_b64_e32 v[118:119], v[2:3]
	v_mov_b64_e32 v[114:115], v[2:3]
	v_mov_b64_e32 v[110:111], v[2:3]
	v_mov_b64_e32 v[106:107], v[2:3]
	v_mov_b64_e32 v[102:103], v[2:3]
	v_mov_b64_e32 v[98:99], v[2:3]
	v_mov_b64_e32 v[94:95], v[2:3]
	v_mov_b64_e32 v[90:91], v[2:3]
	v_mov_b64_e32 v[86:87], v[2:3]
	v_mov_b64_e32 v[82:83], v[2:3]
	v_mov_b64_e32 v[78:79], v[2:3]
	v_mov_b64_e32 v[74:75], v[2:3]
	v_mov_b64_e32 v[70:71], v[2:3]
	v_mov_b64_e32 v[66:67], v[2:3]
	v_mov_b64_e32 v[62:63], v[2:3]
	v_mov_b64_e32 v[58:59], v[2:3]
	v_mov_b64_e32 v[54:55], v[2:3]
	v_mov_b64_e32 v[50:51], v[2:3]
	v_mov_b64_e32 v[46:47], v[2:3]
	v_mov_b64_e32 v[42:43], v[2:3]
	v_mov_b64_e32 v[38:39], v[2:3]
	v_mov_b64_e32 v[34:35], v[2:3]
	v_mov_b64_e32 v[30:31], v[2:3]
	v_mov_b64_e32 v[26:27], v[2:3]
	v_mov_b64_e32 v[22:23], v[2:3]
	v_mov_b64_e32 v[18:19], v[2:3]
	v_mov_b64_e32 v[14:15], v[2:3]
	v_mov_b64_e32 v[10:11], v[2:3]
	v_mov_b64_e32 v[6:7], v[2:3]
	s_mov_b32 s71, s0
	v_readlane_b32 s0, v242, 0
	v_mov_b32_e32 v189, v1
	v_mov_b32_e32 v191, v1
	s_mov_b32 s70, 0
	v_mov_b64_e32 v[128:129], v[0:1]
	v_mov_b64_e32 v[124:125], v[0:1]
	v_mov_b64_e32 v[120:121], v[0:1]
	v_mov_b64_e32 v[116:117], v[0:1]
	v_mov_b64_e32 v[112:113], v[0:1]
	v_mov_b64_e32 v[108:109], v[0:1]
	v_mov_b64_e32 v[104:105], v[0:1]
	v_mov_b64_e32 v[100:101], v[0:1]
	v_mov_b64_e32 v[96:97], v[0:1]
	v_mov_b64_e32 v[92:93], v[0:1]
	v_mov_b64_e32 v[88:89], v[0:1]
	v_mov_b64_e32 v[84:85], v[0:1]
	v_mov_b64_e32 v[80:81], v[0:1]
	v_mov_b64_e32 v[76:77], v[0:1]
	v_mov_b64_e32 v[72:73], v[0:1]
	v_mov_b64_e32 v[68:69], v[0:1]
	v_mov_b64_e32 v[64:65], v[0:1]
	v_mov_b64_e32 v[60:61], v[0:1]
	v_mov_b64_e32 v[56:57], v[0:1]
	v_mov_b64_e32 v[52:53], v[0:1]
	v_mov_b64_e32 v[48:49], v[0:1]
	v_mov_b64_e32 v[44:45], v[0:1]
	v_mov_b64_e32 v[40:41], v[0:1]
	v_mov_b64_e32 v[36:37], v[0:1]
	v_mov_b64_e32 v[32:33], v[0:1]
	v_mov_b64_e32 v[28:29], v[0:1]
	v_mov_b64_e32 v[24:25], v[0:1]
	v_mov_b64_e32 v[20:21], v[0:1]
	v_mov_b64_e32 v[16:17], v[0:1]
	v_mov_b64_e32 v[12:13], v[0:1]
	v_mov_b64_e32 v[8:9], v[0:1]
	v_mov_b64_e32 v[4:5], v[0:1]
	s_mov_b32 s72, s0
	s_mov_b32 s94, 0
	s_barrier
	v_readlane_b32 s1, v242, 1
	s_branch .LBB0_892

.LBB0_903:
	s_add_u32 s24, s30, 0xfff00080
	s_addc_u32 s25, s31, -1
	s_add_i32 s29, 0, 0x10000
	v_add_u32_e32 v0, s29, v204
	ds_read_b128 v[132:135], v0
	ds_read_b128 v[136:139], v0 offset:1024
	ds_read_b128 v[140:143], v0 offset:2048
	ds_read_b128 v[144:147], v0 offset:3072
	s_cmp_eq_u32 s27, 28
	s_cselect_b32 s35, s1, s25
	s_cselect_b32 s34, s0, s24
	s_cselect_b32 s25, s39, s3
	s_cselect_b32 s24, s38, s2
	v_lshl_add_u64 v[2:3], s[30:31], 0, v[188:189]
	s_add_i32 m0, s46, 0xc000
	ds_read_b128 v[148:151], v206
	ds_read_b128 v[152:155], v206 offset:1024
	ds_read_b128 v[156:159], v206 offset:2048
	ds_read_b128 v[160:163], v206 offset:3072
	ds_read_b128 v[164:167], v206 offset:4096
	ds_read_b128 v[168:171], v206 offset:5120
	ds_read_b128 v[208:211], v206 offset:6144
	ds_read_b128 v[212:215], v206 offset:7168
	global_load_lds_dwordx4 v[2:3], off
	v_lshl_add_u64 v[2:3], s[30:31], 0, v[190:191]
	s_add_i32 m0, s46, 0xe000
	s_nop 0
	global_load_lds_dwordx4 v[2:3], off
	v_add_u32_e32 v0, 0x14000, v204
	ds_read_b128 v[216:219], v0
	ds_read_b128 v[220:223], v0 offset:1024
	ds_read_b128 v[224:227], v0 offset:2048
	ds_read_b128 v[228:231], v0 offset:3072
	s_waitcnt lgkmcnt(0)
	s_barrier
	s_setprio 1
	v_mfma_f32_16x16x32_bf16 v[2:5], v[132:135], v[148:151], v[4:7]
	v_mfma_f32_16x16x32_bf16 v[6:9], v[140:143], v[148:151], v[8:11]
	v_mfma_f32_16x16x32_bf16 v[12:15], v[132:135], v[156:159], v[12:15]
	v_mfma_f32_16x16x32_bf16 v[16:19], v[140:143], v[156:159], v[16:19]
	v_mfma_f32_16x16x32_bf16 v[20:23], v[132:135], v[164:167], v[20:23]
	v_mfma_f32_16x16x32_bf16 v[24:27], v[140:143], v[164:167], v[24:27]
	v_mfma_f32_16x16x32_bf16 v[28:31], v[132:135], v[208:211], v[28:31]
	v_mfma_f32_16x16x32_bf16 v[32:35], v[140:143], v[208:211], v[32:35]
	v_mfma_f32_16x16x32_bf16 v[2:5], v[136:139], v[152:155], v[2:5]
	v_mfma_f32_16x16x32_bf16 v[8:11], v[144:147], v[152:155], v[6:9]
	v_mfma_f32_16x16x32_bf16 v[12:15], v[136:139], v[160:163], v[12:15]
	v_mfma_f32_16x16x32_bf16 v[16:19], v[144:147], v[160:163], v[16:19]
	v_mfma_f32_16x16x32_bf16 v[20:23], v[136:139], v[168:171], v[20:23]
	v_mfma_f32_16x16x32_bf16 v[24:27], v[144:147], v[168:171], v[24:27]
	v_mfma_f32_16x16x32_bf16 v[28:31], v[136:139], v[212:215], v[28:31]
	v_mfma_f32_16x16x32_bf16 v[32:35], v[144:147], v[212:215], v[32:35]
	v_mfma_f32_16x16x32_bf16 v[36:39], v[216:219], v[148:151], v[36:39]
	v_mfma_f32_16x16x32_bf16 v[40:43], v[224:227], v[148:151], v[40:43]
	v_mfma_f32_16x16x32_bf16 v[44:47], v[216:219], v[156:159], v[44:47]
	v_mfma_f32_16x16x32_bf16 v[48:51], v[224:227], v[156:159], v[48:51]
	v_mfma_f32_16x16x32_bf16 v[52:55], v[216:219], v[164:167], v[52:55]
	v_mfma_f32_16x16x32_bf16 v[56:59], v[224:227], v[164:167], v[56:59]
	v_mfma_f32_16x16x32_bf16 v[60:63], v[216:219], v[208:211], v[60:63]
	v_mfma_f32_16x16x32_bf16 v[64:67], v[224:227], v[208:211], v[64:67]
	v_mfma_f32_16x16x32_bf16 v[36:39], v[220:223], v[152:155], v[36:39]
	v_mfma_f32_16x16x32_bf16 v[40:43], v[228:231], v[152:155], v[40:43]
	v_mfma_f32_16x16x32_bf16 v[44:47], v[220:223], v[160:163], v[44:47]
	v_mfma_f32_16x16x32_bf16 v[48:51], v[228:231], v[160:163], v[48:51]
	v_mfma_f32_16x16x32_bf16 v[52:55], v[220:223], v[168:171], v[52:55]
	v_mfma_f32_16x16x32_bf16 v[56:59], v[228:231], v[168:171], v[56:59]
	v_mfma_f32_16x16x32_bf16 v[60:63], v[220:223], v[212:215], v[60:63]
	v_mfma_f32_16x16x32_bf16 v[64:67], v[228:231], v[212:215], v[64:67]
	s_setprio 0
	s_barrier
	s_add_i32 s73, 0, 0x14000
	s_add_i32 s29, s29, s41
	v_lshl_add_u64 v[232:233], s[24:25], 0, v[184:185]
	s_mov_b32 m0, s29
	s_nop 0
	global_load_lds_dwordx4 v[232:233], off
	v_lshl_add_u64 v[234:235], s[24:25], 0, v[180:181]
	s_add_i32 m0, s29, 0x2000
	s_nop 0
	global_load_lds_dwordx4 v[234:235], off
	s_mov_b32 m0, s46
	v_lshl_add_u64 v[236:237], s[34:35], 0, v[186:187]
	ds_read_b128 v[148:151], v206 offset:16384
	ds_read_b128 v[152:155], v206 offset:17408
	ds_read_b128 v[156:159], v206 offset:18432
	ds_read_b128 v[160:163], v206 offset:19456
	ds_read_b128 v[164:167], v206 offset:20480
	ds_read_b128 v[168:171], v206 offset:21504
	ds_read_b128 v[208:211], v206 offset:22528
	ds_read_b128 v[212:215], v206 offset:23552
	global_load_lds_dwordx4 v[236:237], off
	v_lshl_add_u64 v[238:239], s[34:35], 0, v[182:183]
	s_mov_b32 m0, s47
	s_nop 0
	global_load_lds_dwordx4 v[238:239], off
	s_add_u32 s74, s24, 0x100000
	s_addc_u32 s75, s25, 0
	s_add_i32 s29, s73, s41
	v_lshl_add_u64 v[6:7], s[74:75], 0, v[184:185]
	s_mov_b32 m0, s29
	s_nop 0
	global_load_lds_dwordx4 v[6:7], off
	v_lshl_add_u64 v[6:7], s[74:75], 0, v[180:181]
	s_add_i32 m0, s29, 0x2000
	s_nop 0
	global_load_lds_dwordx4 v[6:7], off
	s_waitcnt vmcnt(6)
	s_waitcnt lgkmcnt(0)
	s_barrier
	s_setprio 1
	v_mfma_f32_16x16x32_bf16 v[68:71], v[132:135], v[148:151], v[68:71]
	v_mfma_f32_16x16x32_bf16 v[72:75], v[140:143], v[148:151], v[72:75]
	v_mfma_f32_16x16x32_bf16 v[76:79], v[132:135], v[156:159], v[76:79]
	v_mfma_f32_16x16x32_bf16 v[80:83], v[140:143], v[156:159], v[80:83]
	v_mfma_f32_16x16x32_bf16 v[84:87], v[132:135], v[164:167], v[84:87]
	v_mfma_f32_16x16x32_bf16 v[88:91], v[140:143], v[164:167], v[88:91]
	v_mfma_f32_16x16x32_bf16 v[92:95], v[132:135], v[208:211], v[92:95]
	v_mfma_f32_16x16x32_bf16 v[96:99], v[140:143], v[208:211], v[96:99]
	v_mfma_f32_16x16x32_bf16 v[68:71], v[136:139], v[152:155], v[68:71]
	v_mfma_f32_16x16x32_bf16 v[72:75], v[144:147], v[152:155], v[72:75]
	v_mfma_f32_16x16x32_bf16 v[76:79], v[136:139], v[160:163], v[76:79]
	v_mfma_f32_16x16x32_bf16 v[80:83], v[144:147], v[160:163], v[80:83]
	v_mfma_f32_16x16x32_bf16 v[84:87], v[136:139], v[168:171], v[84:87]
	v_mfma_f32_16x16x32_bf16 v[88:91], v[144:147], v[168:171], v[88:91]
	v_mfma_f32_16x16x32_bf16 v[92:95], v[136:139], v[212:215], v[92:95]
	v_mfma_f32_16x16x32_bf16 v[96:99], v[144:147], v[212:215], v[96:99]
	v_mfma_f32_16x16x32_bf16 v[100:103], v[216:219], v[148:151], v[100:103]
	v_mfma_f32_16x16x32_bf16 v[104:107], v[224:227], v[148:151], v[104:107]
	v_mfma_f32_16x16x32_bf16 v[108:111], v[216:219], v[156:159], v[108:111]
	v_mfma_f32_16x16x32_bf16 v[112:115], v[224:227], v[156:159], v[112:115]
	v_mfma_f32_16x16x32_bf16 v[116:119], v[216:219], v[164:167], v[116:119]
	v_mfma_f32_16x16x32_bf16 v[120:123], v[224:227], v[164:167], v[120:123]
	v_mfma_f32_16x16x32_bf16 v[124:127], v[216:219], v[208:211], v[124:127]
	v_mfma_f32_16x16x32_bf16 v[128:131], v[224:227], v[208:211], v[128:131]
	v_mfma_f32_16x16x32_bf16 v[100:103], v[220:223], v[152:155], v[100:103]
	v_mfma_f32_16x16x32_bf16 v[104:107], v[228:231], v[152:155], v[104:107]
	v_mfma_f32_16x16x32_bf16 v[108:111], v[220:223], v[160:163], v[108:111]
	v_mfma_f32_16x16x32_bf16 v[112:115], v[228:231], v[160:163], v[112:115]
	v_mfma_f32_16x16x32_bf16 v[116:119], v[220:223], v[168:171], v[116:119]
	v_mfma_f32_16x16x32_bf16 v[120:123], v[228:231], v[168:171], v[120:123]
	v_mfma_f32_16x16x32_bf16 v[124:127], v[220:223], v[212:215], v[124:127]
	v_mfma_f32_16x16x32_bf16 v[128:131], v[228:231], v[212:215], v[128:131]
	s_setprio 0
	s_add_i32 s29, 0, 0x18000
	v_add_u32_e32 v0, s29, v204
	s_barrier
	ds_read_b128 v[132:135], v0
	ds_read_b128 v[136:139], v0 offset:1024
	ds_read_b128 v[140:143], v0 offset:2048
	ds_read_b128 v[144:147], v0 offset:3072
	s_add_u32 s34, s34, 0x100000
	s_addc_u32 s35, s35, 0
	s_mov_b32 m0, s50
	v_lshl_add_u64 v[6:7], s[34:35], 0, v[186:187]
	ds_read_b128 v[148:151], v206 offset:32768
	ds_read_b128 v[152:155], v206 offset:33792
	ds_read_b128 v[156:159], v206 offset:34816
	ds_read_b128 v[160:163], v206 offset:35840
	ds_read_b128 v[164:167], v206 offset:36864
	ds_read_b128 v[168:171], v206 offset:37888
	ds_read_b128 v[208:211], v206 offset:38912
	ds_read_b128 v[212:215], v206 offset:39936
	global_load_lds_dwordx4 v[6:7], off
	v_lshl_add_u64 v[6:7], s[34:35], 0, v[182:183]
	s_mov_b32 m0, s51
	s_nop 0
	global_load_lds_dwordx4 v[6:7], off
	v_add_u32_e32 v0, 0x1c000, v204
	ds_read_b128 v[216:219], v0
	ds_read_b128 v[220:223], v0 offset:1024
	ds_read_b128 v[224:227], v0 offset:2048
	ds_read_b128 v[228:231], v0 offset:3072
	s_waitcnt lgkmcnt(0)
	s_barrier
	s_setprio 1
	v_mfma_f32_16x16x32_bf16 v[2:5], v[132:135], v[148:151], v[2:5]
	v_mfma_f32_16x16x32_bf16 v[8:11], v[140:143], v[148:151], v[8:11]
	v_mfma_f32_16x16x32_bf16 v[12:15], v[132:135], v[156:159], v[12:15]
	v_mfma_f32_16x16x32_bf16 v[16:19], v[140:143], v[156:159], v[16:19]
	v_mfma_f32_16x16x32_bf16 v[20:23], v[132:135], v[164:167], v[20:23]
	v_mfma_f32_16x16x32_bf16 v[24:27], v[140:143], v[164:167], v[24:27]
	v_mfma_f32_16x16x32_bf16 v[28:31], v[132:135], v[208:211], v[28:31]
	v_mfma_f32_16x16x32_bf16 v[32:35], v[140:143], v[208:211], v[32:35]
	v_mfma_f32_16x16x32_bf16 v[4:7], v[136:139], v[152:155], v[2:5]
	v_mfma_f32_16x16x32_bf16 v[8:11], v[144:147], v[152:155], v[8:11]
	v_mfma_f32_16x16x32_bf16 v[12:15], v[136:139], v[160:163], v[12:15]
	v_mfma_f32_16x16x32_bf16 v[16:19], v[144:147], v[160:163], v[16:19]
	v_mfma_f32_16x16x32_bf16 v[20:23], v[136:139], v[168:171], v[20:23]
	v_mfma_f32_16x16x32_bf16 v[24:27], v[144:147], v[168:171], v[24:27]
	v_mfma_f32_16x16x32_bf16 v[28:31], v[136:139], v[212:215], v[28:31]
	v_mfma_f32_16x16x32_bf16 v[32:35], v[144:147], v[212:215], v[32:35]
	v_mfma_f32_16x16x32_bf16 v[36:39], v[216:219], v[148:151], v[36:39]
	v_mfma_f32_16x16x32_bf16 v[40:43], v[224:227], v[148:151], v[40:43]
	v_mfma_f32_16x16x32_bf16 v[44:47], v[216:219], v[156:159], v[44:47]
	v_mfma_f32_16x16x32_bf16 v[48:51], v[224:227], v[156:159], v[48:51]
	v_mfma_f32_16x16x32_bf16 v[52:55], v[216:219], v[164:167], v[52:55]
	v_mfma_f32_16x16x32_bf16 v[56:59], v[224:227], v[164:167], v[56:59]
	v_mfma_f32_16x16x32_bf16 v[60:63], v[216:219], v[208:211], v[60:63]
	v_mfma_f32_16x16x32_bf16 v[64:67], v[224:227], v[208:211], v[64:67]
	v_mfma_f32_16x16x32_bf16 v[36:39], v[220:223], v[152:155], v[36:39]
	v_mfma_f32_16x16x32_bf16 v[40:43], v[228:231], v[152:155], v[40:43]
	v_mfma_f32_16x16x32_bf16 v[44:47], v[220:223], v[160:163], v[44:47]
	v_mfma_f32_16x16x32_bf16 v[48:51], v[228:231], v[160:163], v[48:51]
	v_mfma_f32_16x16x32_bf16 v[52:55], v[220:223], v[168:171], v[52:55]
	v_mfma_f32_16x16x32_bf16 v[56:59], v[228:231], v[168:171], v[56:59]
	v_mfma_f32_16x16x32_bf16 v[60:63], v[220:223], v[212:215], v[60:63]
	v_mfma_f32_16x16x32_bf16 v[64:67], v[228:231], v[212:215], v[64:67]
	s_setprio 0
	s_barrier
; __device__ __forceinline__ float bflo(unsigned w) { return __uint_as_float(w << 16); }
; __device__ __forceinline__ float bfhi(unsigned w) { return __uint_as_float(w & 0xffff0000u); }
; __device__ __forceinline__ unsigned pk2(float lo, float hi) { unsigned r; asm("v_cvt_pk_bf16_f32 %0, %1, %2" : "=v"(r) : "v"(lo), "v"(hi)); return r; }
;     __device__ __forceinline__ void operator()(const f32x4 (&acc)[2][2][4][2], const Unit& u, int wr, int wc, int fr, int fq) const {
;         const int row0 = u.pm * BM + wr * 64 + fr, col0 = u.pn * BM + wc * 32 + 8 * fq;
; #pragma unroll
;         for (int ai = 0; ai < 2; ++ai)
; #pragma unroll
;             for (int m = 0; m < 4; ++m) { const int row = row0 + ai * HALF + m * 16;
; #pragma unroll
;                 for (int bj = 0; bj < 2; ++bj) { const int col = col0 + bj * HALF;
;                     const u32x4 gp = *(const u32x4*)(proj + (size_t)row * NPROJ + C_GP + col);
;                     const f32x4 v0 = acc[ai][bj][m][0], v1 = acc[ai][bj][m][1];
;                     u32x4 w; w.x = pk2(v0[0] * bflo(gp.x), v0[1] * bfhi(gp.x)); w.y = pk2(v0[2] * bflo(gp.y), v0[3] * bfhi(gp.y));
;                     w.z = pk2(v1[0] * bflo(gp.z), v1[1] * bfhi(gp.z)); w.w = pk2(v1[2] * bflo(gp.w), v1[3] * bfhi(gp.w));
;                     *(u32x4*)(merged + (size_t)row * DM + col) = w; } }
	s_add_i32 s34, 0, 0x1c000
	s_add_i32 s29, s29, s41
	v_lshl_add_u64 v[2:3], v[232:233], 0, s[48:49]
	s_mov_b32 m0, s29
	s_nop 0
	global_load_lds_dwordx4 v[2:3], off
	v_lshl_add_u64 v[2:3], v[234:235], 0, s[48:49]
	s_add_i32 m0, s29, 0x2000
	s_nop 0
	global_load_lds_dwordx4 v[2:3], off
	s_mov_b32 m0, s56
	v_lshl_add_u64 v[2:3], v[236:237], 0, s[48:49]
	ds_read_b128 v[148:151], v206 offset:49152
	ds_read_b128 v[152:155], v206 offset:50176
	ds_read_b128 v[156:159], v206 offset:51200
	ds_read_b128 v[160:163], v206 offset:52224
	ds_read_b128 v[164:167], v206 offset:53248
	ds_read_b128 v[168:171], v206 offset:54272
	ds_read_b128 v[208:211], v206 offset:55296
	ds_read_b128 v[212:215], v206 offset:56320
	global_load_lds_dwordx4 v[2:3], off
	v_lshl_add_u64 v[2:3], v[238:239], 0, s[48:49]
	s_mov_b32 m0, s57
	s_nop 0
	global_load_lds_dwordx4 v[2:3], off
	s_add_u32 s24, s24, 0x100080
	s_addc_u32 s25, s25, 0
	s_add_i32 s29, s34, s41
	v_lshl_add_u64 v[2:3], s[24:25], 0, v[184:185]
	s_mov_b32 m0, s29
	s_nop 0
	global_load_lds_dwordx4 v[2:3], off
	v_lshl_add_u64 v[2:3], s[24:25], 0, v[180:181]
	s_add_i32 m0, s29, 0x2000
	s_nop 0
	global_load_lds_dwordx4 v[2:3], off
	s_waitcnt vmcnt(6)
	s_waitcnt lgkmcnt(0)
	s_barrier
	s_setprio 1
	v_mfma_f32_16x16x32_bf16 v[68:71], v[132:135], v[148:151], v[68:71]
	v_mfma_f32_16x16x32_bf16 v[72:75], v[140:143], v[148:151], v[72:75]
	v_mfma_f32_16x16x32_bf16 v[76:79], v[132:135], v[156:159], v[76:79]
	v_mfma_f32_16x16x32_bf16 v[80:83], v[140:143], v[156:159], v[80:83]
	v_mfma_f32_16x16x32_bf16 v[84:87], v[132:135], v[164:167], v[84:87]
	v_mfma_f32_16x16x32_bf16 v[88:91], v[140:143], v[164:167], v[88:91]
	v_mfma_f32_16x16x32_bf16 v[92:95], v[132:135], v[208:211], v[92:95]
	v_mfma_f32_16x16x32_bf16 v[96:99], v[140:143], v[208:211], v[96:99]
	v_mfma_f32_16x16x32_bf16 v[68:71], v[136:139], v[152:155], v[68:71]
	v_mfma_f32_16x16x32_bf16 v[72:75], v[144:147], v[152:155], v[72:75]
	v_mfma_f32_16x16x32_bf16 v[76:79], v[136:139], v[160:163], v[76:79]
	v_mfma_f32_16x16x32_bf16 v[80:83], v[144:147], v[160:163], v[80:83]
	v_mfma_f32_16x16x32_bf16 v[84:87], v[136:139], v[168:171], v[84:87]
	v_mfma_f32_16x16x32_bf16 v[88:91], v[144:147], v[168:171], v[88:91]
	v_mfma_f32_16x16x32_bf16 v[92:95], v[136:139], v[212:215], v[92:95]
	v_mfma_f32_16x16x32_bf16 v[96:99], v[144:147], v[212:215], v[96:99]
	v_mfma_f32_16x16x32_bf16 v[100:103], v[216:219], v[148:151], v[100:103]
	v_mfma_f32_16x16x32_bf16 v[104:107], v[224:227], v[148:151], v[104:107]
	v_mfma_f32_16x16x32_bf16 v[108:111], v[216:219], v[156:159], v[108:111]
	v_mfma_f32_16x16x32_bf16 v[112:115], v[224:227], v[156:159], v[112:115]
	v_mfma_f32_16x16x32_bf16 v[116:119], v[216:219], v[164:167], v[116:119]
	v_mfma_f32_16x16x32_bf16 v[120:123], v[224:227], v[164:167], v[120:123]
	v_mfma_f32_16x16x32_bf16 v[124:127], v[216:219], v[208:211], v[124:127]
	v_mfma_f32_16x16x32_bf16 v[128:131], v[224:227], v[208:211], v[128:131]
	v_mfma_f32_16x16x32_bf16 v[100:103], v[220:223], v[152:155], v[100:103]
	v_mfma_f32_16x16x32_bf16 v[104:107], v[228:231], v[152:155], v[104:107]
	v_mfma_f32_16x16x32_bf16 v[108:111], v[220:223], v[160:163], v[108:111]
	v_mfma_f32_16x16x32_bf16 v[112:115], v[228:231], v[160:163], v[112:115]
	v_mfma_f32_16x16x32_bf16 v[116:119], v[220:223], v[168:171], v[116:119]
	v_mfma_f32_16x16x32_bf16 v[120:123], v[228:231], v[168:171], v[120:123]
	v_mfma_f32_16x16x32_bf16 v[124:127], v[220:223], v[212:215], v[124:127]
	v_mfma_f32_16x16x32_bf16 v[128:131], v[228:231], v[212:215], v[128:131]
	s_setprio 0
	s_add_i32 s27, s27, 2
	s_add_u32 s30, s30, 0x100
	s_addc_u32 s31, s31, 0
	s_add_u32 s2, s2, 0x100
	s_addc_u32 s3, s3, 0
	s_cmp_gt_u32 s27, 29
	s_barrier
	s_cbranch_scc0 .LBB0_903
	s_cmp_lg_u32 s70, 0
	s_cselect_b64 s[30:31], -1, 0
	v_lshl_add_u32 v144, s72, 8, v203
	v_lshl_or_b32 v146, s71, 8, v205
	s_and_b64 vcc, exec, s[30:31]
	v_ashrrev_i32_e32 v147, 31, v146
	v_or_b32_e32 v142, 16, v144
	v_or_b32_e32 v140, 32, v144
	v_or_b32_e32 v138, 48, v144
	v_add_u32_e32 v136, 0x80, v144
	v_add_u32_e32 v134, 0x90, v144
	v_add_u32_e32 v132, 0xa0, v144
	v_add_u32_e32 v2, 0xb0, v144
	s_cbranch_vccz .LBB0_910
	v_mov_b64_e32 v[150:151], s[92:93]
	v_mad_i64_i32 v[148:149], s[2:3], v144, s91, v[150:151]
	v_lshl_add_u64 v[158:159], v[148:149], 0, s[76:77]
	v_lshlrev_b64 v[148:149], 1, v[146:147]
	v_lshl_add_u64 v[152:153], v[158:159], 0, v[148:149]
	v_mov_b32_e32 v170, v152
	v_mov_b32_e32 v171, v153
	s_mov_b32 s74, 0x0
	s_mov_b32 s75, 0
	v_lshl_add_u64 v[208:209], v[170:171], 0, s[74:75]
	global_load_dwordx4 v[208:211], v[208:209], off
	s_mov_b32 s74, 0x100
	s_mov_b32 s75, 0
	v_lshl_add_u64 v[212:213], v[170:171], 0, s[74:75]
	global_load_dwordx4 v[212:215], v[212:213], off
	s_mov_b32 s74, 0x6a000
	s_mov_b32 s75, 0
	v_lshl_add_u64 v[216:217], v[170:171], 0, s[74:75]
	global_load_dwordx4 v[216:219], v[216:217], off
	s_mov_b32 s74, 0x6a100
	s_mov_b32 s75, 0
	v_lshl_add_u64 v[220:221], v[170:171], 0, s[74:75]
	global_load_dwordx4 v[220:223], v[220:221], off
	s_mov_b32 s74, 0xd4000
	s_mov_b32 s75, 0
	v_lshl_add_u64 v[224:225], v[170:171], 0, s[74:75]
	global_load_dwordx4 v[224:227], v[224:225], off
	s_mov_b32 s74, 0xd4100
	s_mov_b32 s75, 0
	v_lshl_add_u64 v[228:229], v[170:171], 0, s[74:75]
	global_load_dwordx4 v[228:231], v[228:229], off
	s_mov_b32 s74, 0x13e000
	s_mov_b32 s75, 0
	v_lshl_add_u64 v[232:233], v[170:171], 0, s[74:75]
	global_load_dwordx4 v[232:235], v[232:233], off
	s_mov_b32 s74, 0x13e100
	s_mov_b32 s75, 0
	v_lshl_add_u64 v[236:237], v[170:171], 0, s[74:75]
	global_load_dwordx4 v[236:239], v[236:237], off
	s_mov_b32 s74, 0x350000
	s_mov_b32 s75, 0
	v_lshl_add_u64 v[166:167], v[170:171], 0, s[74:75]
	global_load_dwordx4 v[166:169], v[166:167], off
	s_mov_b32 s74, 0x350100
	s_mov_b32 s75, 0
	v_lshl_add_u64 v[246:247], v[170:171], 0, s[74:75]
	global_load_dwordx4 v[246:249], v[246:247], off
	s_mov_b32 s74, 0x3ba000
	s_mov_b32 s75, 0
	v_lshl_add_u64 v[250:251], v[170:171], 0, s[74:75]
	global_load_dwordx4 v[250:253], v[250:251], off
	v_ashrrev_i32_e32 v145, 31, v144
	v_readlane_b32 s4, v244, 47
	v_lshlrev_b64 v[156:157], 12, v[144:145]
	v_readlane_b32 s8, v244, 51
	v_readlane_b32 s9, v244, 52
	v_ashrrev_i32_e32 v143, 31, v142
	v_lshlrev_b64 v[162:163], 12, v[142:143]
	v_lshl_add_u64 v[156:157], s[8:9], 0, v[156:157]
	v_lshl_add_u64 v[160:161], v[156:157], 0, v[148:149]
	v_ashrrev_i32_e32 v141, 31, v140
	v_ashrrev_i32_e32 v139, 31, v138
	v_ashrrev_i32_e32 v137, 31, v136
	v_ashrrev_i32_e32 v135, 31, v134
	v_ashrrev_i32_e32 v133, 31, v132
	v_readlane_b32 s5, v244, 48
	v_readlane_b32 s6, v244, 49
	v_readlane_b32 s7, v244, 50
	v_readlane_b32 s10, v244, 53
	v_readlane_b32 s11, v244, 54
	s_waitcnt vmcnt(10)
; __device__ __forceinline__ float bflo(unsigned w) { return __uint_as_float(w << 16); }
; __device__ __forceinline__ float bfhi(unsigned w) { return __uint_as_float(w & 0xffff0000u); }
; __device__ __forceinline__ unsigned pk2(float lo, float hi) { unsigned r; asm("v_cvt_pk_bf16_f32 %0, %1, %2" : "=v"(r) : "v"(lo), "v"(hi)); return r; }
;     __device__ __forceinline__ void operator()(const f32x4 (&acc)[2][2][4][2], const Unit& u, int wr, int wc, int fr, int fq) const {
;         const int row0 = u.pm * BM + wr * 64 + fr, col0 = u.pn * BM + wc * 32 + 8 * fq;
; #pragma unroll
;         for (int ai = 0; ai < 2; ++ai)
; #pragma unroll
;             for (int m = 0; m < 4; ++m) { const int row = row0 + ai * HALF + m * 16;
; #pragma unroll
;                 for (int bj = 0; bj < 2; ++bj) { const int col = col0 + bj * HALF;
;                     const u32x4 gp = *(const u32x4*)(proj + (size_t)row * NPROJ + C_GP + col);
;                     const f32x4 v0 = acc[ai][bj][m][0], v1 = acc[ai][bj][m][1];
;                     u32x4 w; w.x = pk2(v0[0] * bflo(gp.x), v0[1] * bfhi(gp.x)); w.y = pk2(v0[2] * bflo(gp.y), v0[3] * bfhi(gp.y));
;                     w.z = pk2(v1[0] * bflo(gp.z), v1[1] * bfhi(gp.z)); w.w = pk2(v1[2] * bflo(gp.w), v1[3] * bfhi(gp.w));
;                     *(u32x4*)(merged + (size_t)row * DM + col) = w; } }
	v_mov_b32_e32 v152, v208
	v_mov_b32_e32 v153, v209
	v_mov_b32_e32 v154, v210
	v_mov_b32_e32 v155, v211
	s_mov_b32 s74, 0x3ba100
	s_mov_b32 s75, 0
	v_lshl_add_u64 v[208:209], v[170:171], 0, s[74:75]
	global_load_dwordx4 v[208:211], v[208:209], off
	v_lshlrev_b32_e32 v0, 16, v152
	v_and_b32_e32 v3, 0xffff0000, v152
	v_mul_f32_e32 v0, v4, v0
	v_mul_f32_e32 v3, v5, v3
	v_cvt_pk_bf16_f32 v152, v0, v3
	v_lshlrev_b32_e32 v0, 16, v153
	v_and_b32_e32 v3, 0xffff0000, v153
	v_mul_f32_e32 v0, v6, v0
	v_mul_f32_e32 v3, v7, v3
	v_cvt_pk_bf16_f32 v153, v0, v3
	v_lshlrev_b32_e32 v0, 16, v154
	v_and_b32_e32 v3, 0xffff0000, v154
	v_mul_f32_e32 v0, v8, v0
	v_mul_f32_e32 v3, v9, v3
	v_cvt_pk_bf16_f32 v154, v0, v3
	v_lshlrev_b32_e32 v0, 16, v155
	v_and_b32_e32 v3, 0xffff0000, v155
	v_mul_f32_e32 v0, v10, v0
	v_mul_f32_e32 v3, v11, v3
	v_cvt_pk_bf16_f32 v155, v0, v3
	global_store_dwordx4 v[160:161], v[152:155], off
	s_nop 1
	v_or_b32_e32 v152, 0x80, v146
	v_ashrrev_i32_e32 v153, 31, v152
	v_lshlrev_b64 v[152:153], 1, v[152:153]
	v_lshl_add_u64 v[154:155], v[158:159], 0, v[152:153]
	s_waitcnt vmcnt(11)
	v_mov_b32_e32 v154, v212
	v_mov_b32_e32 v155, v213
	v_mov_b32_e32 v156, v214
	v_mov_b32_e32 v157, v215
	s_mov_b32 s74, 0x424000
	s_mov_b32 s75, 0
	v_lshl_add_u64 v[212:213], v[170:171], 0, s[74:75]
	global_load_dwordx4 v[212:215], v[212:213], off
	v_lshlrev_b32_e32 v0, 16, v154
	v_and_b32_e32 v3, 0xffff0000, v154
	v_mul_f32_e32 v0, v36, v0
	v_mul_f32_e32 v3, v37, v3
	v_cvt_pk_bf16_f32 v154, v0, v3
	v_lshlrev_b32_e32 v0, 16, v155
	v_and_b32_e32 v3, 0xffff0000, v155
	v_mul_f32_e32 v0, v38, v0
	v_mul_f32_e32 v3, v39, v3
	v_cvt_pk_bf16_f32 v155, v0, v3
	v_lshlrev_b32_e32 v0, 16, v156
	v_and_b32_e32 v3, 0xffff0000, v156
	v_mul_f32_e32 v0, v40, v0
	v_mul_f32_e32 v3, v41, v3
	v_cvt_pk_bf16_f32 v156, v0, v3
	v_lshlrev_b32_e32 v0, 16, v157
	v_and_b32_e32 v3, 0xffff0000, v157
	v_mul_f32_e32 v0, v42, v0
	v_mul_f32_e32 v3, v43, v3
	v_cvt_pk_bf16_f32 v157, v0, v3
	global_store_dwordx4 v[160:161], v[154:157], off offset:256
	s_nop 1
	v_mad_i64_i32 v[154:155], s[2:3], v142, s91, v[150:151]
	v_lshl_add_u64 v[164:165], v[154:155], 0, s[76:77]
	v_lshl_add_u64 v[154:155], v[164:165], 0, v[148:149]
	s_waitcnt vmcnt(12)
	v_mov_b32_e32 v154, v216
	v_mov_b32_e32 v155, v217
	v_mov_b32_e32 v156, v218
	v_mov_b32_e32 v157, v219
	s_mov_b32 s74, 0x424100
	s_mov_b32 s75, 0
	v_lshl_add_u64 v[216:217], v[170:171], 0, s[74:75]
	global_load_dwordx4 v[216:219], v[216:217], off
	v_lshlrev_b32_e32 v0, 16, v154
	v_and_b32_e32 v3, 0xffff0000, v154
	v_mul_f32_e32 v0, v12, v0
	v_mul_f32_e32 v3, v13, v3
	v_cvt_pk_bf16_f32 v158, v0, v3
	v_lshlrev_b32_e32 v0, 16, v155
	v_and_b32_e32 v3, 0xffff0000, v155
	v_mul_f32_e32 v0, v14, v0
	v_mul_f32_e32 v3, v15, v3
	v_cvt_pk_bf16_f32 v159, v0, v3
	v_lshlrev_b32_e32 v0, 16, v156
	v_and_b32_e32 v3, 0xffff0000, v156
	v_mul_f32_e32 v0, v16, v0
	v_mul_f32_e32 v3, v17, v3
	v_lshl_add_u64 v[154:155], s[8:9], 0, v[162:163]
	v_cvt_pk_bf16_f32 v160, v0, v3
	v_lshlrev_b32_e32 v0, 16, v157
	v_and_b32_e32 v3, 0xffff0000, v157
	v_lshl_add_u64 v[154:155], v[154:155], 0, v[148:149]
	v_lshl_add_u64 v[156:157], v[164:165], 0, v[152:153]
	v_mul_f32_e32 v0, v18, v0
	v_mul_f32_e32 v3, v19, v3
	v_cvt_pk_bf16_f32 v161, v0, v3
	global_store_dwordx4 v[154:155], v[158:161], off
	v_lshlrev_b64 v[162:163], 12, v[140:141]
	s_waitcnt vmcnt(13)
	v_mov_b32_e32 v156, v220
	v_mov_b32_e32 v157, v221
	v_mov_b32_e32 v158, v222
	v_mov_b32_e32 v159, v223
	s_mov_b32 s74, 0x48e000
	s_mov_b32 s75, 0
	v_lshl_add_u64 v[220:221], v[170:171], 0, s[74:75]
	global_load_dwordx4 v[220:223], v[220:221], off
	v_lshlrev_b32_e32 v0, 16, v156
	v_and_b32_e32 v3, 0xffff0000, v156
	v_mul_f32_e32 v0, v44, v0
	v_mul_f32_e32 v3, v45, v3
	v_cvt_pk_bf16_f32 v156, v0, v3
	v_lshlrev_b32_e32 v0, 16, v157
	v_and_b32_e32 v3, 0xffff0000, v157
	v_mul_f32_e32 v0, v46, v0
	v_mul_f32_e32 v3, v47, v3
	v_cvt_pk_bf16_f32 v157, v0, v3
	v_lshlrev_b32_e32 v0, 16, v158
	v_and_b32_e32 v3, 0xffff0000, v158
	v_mul_f32_e32 v0, v48, v0
	v_mul_f32_e32 v3, v49, v3
	v_cvt_pk_bf16_f32 v158, v0, v3
	v_lshlrev_b32_e32 v0, 16, v159
	v_and_b32_e32 v3, 0xffff0000, v159
	v_mul_f32_e32 v0, v50, v0
	v_mul_f32_e32 v3, v51, v3
	v_cvt_pk_bf16_f32 v159, v0, v3
	global_store_dwordx4 v[154:155], v[156:159], off offset:256
	v_mad_i64_i32 v[154:155], s[2:3], v140, s91, v[150:151]
	v_lshl_add_u64 v[164:165], v[154:155], 0, s[76:77]
	v_lshl_add_u64 v[154:155], v[164:165], 0, v[148:149]
	s_waitcnt vmcnt(14)
	v_mov_b32_e32 v154, v224
	v_mov_b32_e32 v155, v225
	v_mov_b32_e32 v156, v226
	v_mov_b32_e32 v157, v227
	s_mov_b32 s74, 0x48e100
	s_mov_b32 s75, 0
	v_lshl_add_u64 v[224:225], v[170:171], 0, s[74:75]
	global_load_dwordx4 v[224:227], v[224:225], off
	v_lshlrev_b32_e32 v0, 16, v154
	v_and_b32_e32 v3, 0xffff0000, v154
	v_mul_f32_e32 v0, v20, v0
	v_mul_f32_e32 v3, v21, v3
	v_cvt_pk_bf16_f32 v158, v0, v3
	v_lshlrev_b32_e32 v0, 16, v155
	v_and_b32_e32 v3, 0xffff0000, v155
	v_mul_f32_e32 v0, v22, v0
	v_mul_f32_e32 v3, v23, v3
	v_cvt_pk_bf16_f32 v159, v0, v3
	v_lshlrev_b32_e32 v0, 16, v156
	v_and_b32_e32 v3, 0xffff0000, v156
	v_mul_f32_e32 v0, v24, v0
	v_mul_f32_e32 v3, v25, v3
	v_lshl_add_u64 v[154:155], s[8:9], 0, v[162:163]
	v_cvt_pk_bf16_f32 v160, v0, v3
	v_lshlrev_b32_e32 v0, 16, v157
	v_and_b32_e32 v3, 0xffff0000, v157
	v_lshl_add_u64 v[154:155], v[154:155], 0, v[148:149]
	v_lshl_add_u64 v[156:157], v[164:165], 0, v[152:153]
	v_mul_f32_e32 v0, v26, v0
	v_mul_f32_e32 v3, v27, v3
	v_cvt_pk_bf16_f32 v161, v0, v3
	global_store_dwordx4 v[154:155], v[158:161], off
	v_lshlrev_b64 v[162:163], 12, v[138:139]
	s_waitcnt vmcnt(15)
; __device__ __forceinline__ float bflo(unsigned w) { return __uint_as_float(w << 16); }
; __device__ __forceinline__ float bfhi(unsigned w) { return __uint_as_float(w & 0xffff0000u); }
; __device__ __forceinline__ unsigned pk2(float lo, float hi) { unsigned r; asm("v_cvt_pk_bf16_f32 %0, %1, %2" : "=v"(r) : "v"(lo), "v"(hi)); return r; }
;     __device__ __forceinline__ void operator()(const f32x4 (&acc)[2][2][4][2], const Unit& u, int wr, int wc, int fr, int fq) const {
;         const int row0 = u.pm * BM + wr * 64 + fr, col0 = u.pn * BM + wc * 32 + 8 * fq;
; #pragma unroll
;         for (int ai = 0; ai < 2; ++ai)
; #pragma unroll
;             for (int m = 0; m < 4; ++m) { const int row = row0 + ai * HALF + m * 16;
; #pragma unroll
;                 for (int bj = 0; bj < 2; ++bj) { const int col = col0 + bj * HALF;
;                     const u32x4 gp = *(const u32x4*)(proj + (size_t)row * NPROJ + C_GP + col);
;                     const f32x4 v0 = acc[ai][bj][m][0], v1 = acc[ai][bj][m][1];
;                     u32x4 w; w.x = pk2(v0[0] * bflo(gp.x), v0[1] * bfhi(gp.x)); w.y = pk2(v0[2] * bflo(gp.y), v0[3] * bfhi(gp.y));
;                     w.z = pk2(v1[0] * bflo(gp.z), v1[1] * bfhi(gp.z)); w.w = pk2(v1[2] * bflo(gp.w), v1[3] * bfhi(gp.w));
;                     *(u32x4*)(merged + (size_t)row * DM + col) = w; } }
	v_mov_b32_e32 v156, v228
	v_mov_b32_e32 v157, v229
	v_mov_b32_e32 v158, v230
	v_mov_b32_e32 v159, v231
	v_lshlrev_b32_e32 v0, 16, v156
	v_and_b32_e32 v3, 0xffff0000, v156
	v_mul_f32_e32 v0, v52, v0
	v_mul_f32_e32 v3, v53, v3
	v_cvt_pk_bf16_f32 v156, v0, v3
	v_lshlrev_b32_e32 v0, 16, v157
	v_and_b32_e32 v3, 0xffff0000, v157
	v_mul_f32_e32 v0, v54, v0
	v_mul_f32_e32 v3, v55, v3
	v_cvt_pk_bf16_f32 v157, v0, v3
	v_lshlrev_b32_e32 v0, 16, v158
	v_and_b32_e32 v3, 0xffff0000, v158
	v_mul_f32_e32 v0, v56, v0
	v_mul_f32_e32 v3, v57, v3
	v_cvt_pk_bf16_f32 v158, v0, v3
	v_lshlrev_b32_e32 v0, 16, v159
	v_and_b32_e32 v3, 0xffff0000, v159
	v_mul_f32_e32 v0, v58, v0
	v_mul_f32_e32 v3, v59, v3
	v_cvt_pk_bf16_f32 v159, v0, v3
	global_store_dwordx4 v[154:155], v[156:159], off offset:256
	v_mad_i64_i32 v[154:155], s[2:3], v138, s91, v[150:151]
	v_lshl_add_u64 v[164:165], v[154:155], 0, s[76:77]
	v_lshl_add_u64 v[154:155], v[164:165], 0, v[148:149]
	s_waitcnt vmcnt(15)
	v_mov_b32_e32 v154, v232
	v_mov_b32_e32 v155, v233
	v_mov_b32_e32 v156, v234
	v_mov_b32_e32 v157, v235
	v_lshlrev_b32_e32 v0, 16, v154
	v_and_b32_e32 v3, 0xffff0000, v154
	v_mul_f32_e32 v0, v28, v0
	v_mul_f32_e32 v3, v29, v3
	v_cvt_pk_bf16_f32 v158, v0, v3
	v_lshlrev_b32_e32 v0, 16, v155
	v_and_b32_e32 v3, 0xffff0000, v155
	v_mul_f32_e32 v0, v30, v0
	v_mul_f32_e32 v3, v31, v3
	v_cvt_pk_bf16_f32 v159, v0, v3
	v_lshlrev_b32_e32 v0, 16, v156
	v_and_b32_e32 v3, 0xffff0000, v156
	v_mul_f32_e32 v0, v32, v0
	v_mul_f32_e32 v3, v33, v3
	v_lshl_add_u64 v[154:155], s[8:9], 0, v[162:163]
	v_cvt_pk_bf16_f32 v160, v0, v3
	v_lshlrev_b32_e32 v0, 16, v157
	v_and_b32_e32 v3, 0xffff0000, v157
	v_lshl_add_u64 v[154:155], v[154:155], 0, v[148:149]
	v_lshl_add_u64 v[156:157], v[164:165], 0, v[152:153]
	v_mul_f32_e32 v0, v34, v0
	v_mul_f32_e32 v3, v35, v3
	v_cvt_pk_bf16_f32 v161, v0, v3
	global_store_dwordx4 v[154:155], v[158:161], off
	v_lshlrev_b64 v[162:163], 12, v[136:137]
	s_waitcnt vmcnt(15)
	v_mov_b32_e32 v156, v236
	v_mov_b32_e32 v157, v237
	v_mov_b32_e32 v158, v238
	v_mov_b32_e32 v159, v239
	v_lshlrev_b32_e32 v0, 16, v156
	v_and_b32_e32 v3, 0xffff0000, v156
	v_mul_f32_e32 v0, v60, v0
	v_mul_f32_e32 v3, v61, v3
	v_cvt_pk_bf16_f32 v156, v0, v3
	v_lshlrev_b32_e32 v0, 16, v157
	v_and_b32_e32 v3, 0xffff0000, v157
	v_mul_f32_e32 v0, v62, v0
	v_mul_f32_e32 v3, v63, v3
	v_cvt_pk_bf16_f32 v157, v0, v3
	v_lshlrev_b32_e32 v0, 16, v158
	v_and_b32_e32 v3, 0xffff0000, v158
	v_mul_f32_e32 v0, v64, v0
	v_mul_f32_e32 v3, v65, v3
	v_cvt_pk_bf16_f32 v158, v0, v3
	v_lshlrev_b32_e32 v0, 16, v159
	v_and_b32_e32 v3, 0xffff0000, v159
	v_mul_f32_e32 v0, v66, v0
	v_mul_f32_e32 v3, v67, v3
	v_cvt_pk_bf16_f32 v159, v0, v3
	global_store_dwordx4 v[154:155], v[156:159], off offset:256
	v_mad_i64_i32 v[154:155], s[2:3], v136, s91, v[150:151]
	v_lshl_add_u64 v[164:165], v[154:155], 0, s[76:77]
	v_lshl_add_u64 v[154:155], v[164:165], 0, v[148:149]
	s_waitcnt vmcnt(15)
	v_mov_b32_e32 v154, v166
	v_mov_b32_e32 v155, v167
	v_mov_b32_e32 v156, v168
	v_mov_b32_e32 v157, v169
	v_lshlrev_b32_e32 v0, 16, v154
	v_and_b32_e32 v3, 0xffff0000, v154
	v_mul_f32_e32 v0, v68, v0
	v_mul_f32_e32 v3, v69, v3
	v_cvt_pk_bf16_f32 v158, v0, v3
	v_lshlrev_b32_e32 v0, 16, v155
	v_and_b32_e32 v3, 0xffff0000, v155
	v_mul_f32_e32 v0, v70, v0
	v_mul_f32_e32 v3, v71, v3
	v_cvt_pk_bf16_f32 v159, v0, v3
	v_lshlrev_b32_e32 v0, 16, v156
	v_and_b32_e32 v3, 0xffff0000, v156
	v_mul_f32_e32 v0, v72, v0
	v_mul_f32_e32 v3, v73, v3
	v_lshl_add_u64 v[154:155], s[8:9], 0, v[162:163]
	v_cvt_pk_bf16_f32 v160, v0, v3
	v_lshlrev_b32_e32 v0, 16, v157
	v_and_b32_e32 v3, 0xffff0000, v157
	v_lshl_add_u64 v[154:155], v[154:155], 0, v[148:149]
	v_lshl_add_u64 v[156:157], v[164:165], 0, v[152:153]
	v_mul_f32_e32 v0, v74, v0
	v_mul_f32_e32 v3, v75, v3
	v_cvt_pk_bf16_f32 v161, v0, v3
	global_store_dwordx4 v[154:155], v[158:161], off
	v_lshlrev_b64 v[162:163], 12, v[134:135]
	s_waitcnt vmcnt(15)
	v_mov_b32_e32 v156, v246
	v_mov_b32_e32 v157, v247
	v_mov_b32_e32 v158, v248
	v_mov_b32_e32 v159, v249
	v_lshlrev_b32_e32 v0, 16, v156
	v_and_b32_e32 v3, 0xffff0000, v156
	v_mul_f32_e32 v0, v100, v0
	v_mul_f32_e32 v3, v101, v3
	v_cvt_pk_bf16_f32 v156, v0, v3
	v_lshlrev_b32_e32 v0, 16, v157
	v_and_b32_e32 v3, 0xffff0000, v157
	v_mul_f32_e32 v0, v102, v0
	v_mul_f32_e32 v3, v103, v3
	v_cvt_pk_bf16_f32 v157, v0, v3
	v_lshlrev_b32_e32 v0, 16, v158
	v_and_b32_e32 v3, 0xffff0000, v158
	v_mul_f32_e32 v0, v104, v0
	v_mul_f32_e32 v3, v105, v3
	v_cvt_pk_bf16_f32 v158, v0, v3
	v_lshlrev_b32_e32 v0, 16, v159
	v_and_b32_e32 v3, 0xffff0000, v159
	v_mul_f32_e32 v0, v106, v0
	v_mul_f32_e32 v3, v107, v3
	v_cvt_pk_bf16_f32 v159, v0, v3
	global_store_dwordx4 v[154:155], v[156:159], off offset:256
	v_mad_i64_i32 v[154:155], s[2:3], v134, s91, v[150:151]
	v_lshl_add_u64 v[164:165], v[154:155], 0, s[76:77]
	v_lshl_add_u64 v[154:155], v[164:165], 0, v[148:149]
	s_waitcnt vmcnt(15)
; __device__ __forceinline__ float bflo(unsigned w) { return __uint_as_float(w << 16); }
; __device__ __forceinline__ float bfhi(unsigned w) { return __uint_as_float(w & 0xffff0000u); }
; __device__ __forceinline__ unsigned pk2(float lo, float hi) { unsigned r; asm("v_cvt_pk_bf16_f32 %0, %1, %2" : "=v"(r) : "v"(lo), "v"(hi)); return r; }
;     __device__ __forceinline__ void operator()(const f32x4 (&acc)[2][2][4][2], const Unit& u, int wr, int wc, int fr, int fq) const {
;         const int row0 = u.pm * BM + wr * 64 + fr, col0 = u.pn * BM + wc * 32 + 8 * fq;
; #pragma unroll
;         for (int ai = 0; ai < 2; ++ai)
; #pragma unroll
;             for (int m = 0; m < 4; ++m) { const int row = row0 + ai * HALF + m * 16;
; #pragma unroll
;                 for (int bj = 0; bj < 2; ++bj) { const int col = col0 + bj * HALF;
;                     const u32x4 gp = *(const u32x4*)(proj + (size_t)row * NPROJ + C_GP + col);
;                     const f32x4 v0 = acc[ai][bj][m][0], v1 = acc[ai][bj][m][1];
;                     u32x4 w; w.x = pk2(v0[0] * bflo(gp.x), v0[1] * bfhi(gp.x)); w.y = pk2(v0[2] * bflo(gp.y), v0[3] * bfhi(gp.y));
;                     w.z = pk2(v1[0] * bflo(gp.z), v1[1] * bfhi(gp.z)); w.w = pk2(v1[2] * bflo(gp.w), v1[3] * bfhi(gp.w));
;                     *(u32x4*)(merged + (size_t)row * DM + col) = w; } }
	v_mov_b32_e32 v154, v250
	v_mov_b32_e32 v155, v251
	v_mov_b32_e32 v156, v252
	v_mov_b32_e32 v157, v253
	v_lshlrev_b32_e32 v0, 16, v154
	v_and_b32_e32 v3, 0xffff0000, v154
	v_mul_f32_e32 v0, v76, v0
	v_mul_f32_e32 v3, v77, v3
	v_cvt_pk_bf16_f32 v158, v0, v3
	v_lshlrev_b32_e32 v0, 16, v155
	v_and_b32_e32 v3, 0xffff0000, v155
	v_mul_f32_e32 v0, v78, v0
	v_mul_f32_e32 v3, v79, v3
	v_cvt_pk_bf16_f32 v159, v0, v3
	v_lshlrev_b32_e32 v0, 16, v156
	v_and_b32_e32 v3, 0xffff0000, v156
	v_mul_f32_e32 v0, v80, v0
	v_mul_f32_e32 v3, v81, v3
	v_lshl_add_u64 v[154:155], s[8:9], 0, v[162:163]
	v_cvt_pk_bf16_f32 v160, v0, v3
	v_lshlrev_b32_e32 v0, 16, v157
	v_and_b32_e32 v3, 0xffff0000, v157
	v_lshl_add_u64 v[154:155], v[154:155], 0, v[148:149]
	v_lshl_add_u64 v[156:157], v[164:165], 0, v[152:153]
	v_mul_f32_e32 v0, v82, v0
	v_mul_f32_e32 v3, v83, v3
	v_cvt_pk_bf16_f32 v161, v0, v3
	global_store_dwordx4 v[154:155], v[158:161], off
	v_lshlrev_b64 v[162:163], 12, v[132:133]
	s_waitcnt vmcnt(15)
	v_mov_b32_e32 v156, v208
	v_mov_b32_e32 v157, v209
	v_mov_b32_e32 v158, v210
	v_mov_b32_e32 v159, v211
	v_lshlrev_b32_e32 v0, 16, v156
	v_and_b32_e32 v3, 0xffff0000, v156
	v_mul_f32_e32 v0, v108, v0
	v_mul_f32_e32 v3, v109, v3
	v_cvt_pk_bf16_f32 v156, v0, v3
	v_lshlrev_b32_e32 v0, 16, v157
	v_and_b32_e32 v3, 0xffff0000, v157
	v_mul_f32_e32 v0, v110, v0
	v_mul_f32_e32 v3, v111, v3
	v_cvt_pk_bf16_f32 v157, v0, v3
	v_lshlrev_b32_e32 v0, 16, v158
	v_and_b32_e32 v3, 0xffff0000, v158
	v_mul_f32_e32 v0, v112, v0
	v_mul_f32_e32 v3, v113, v3
	v_cvt_pk_bf16_f32 v158, v0, v3
	v_lshlrev_b32_e32 v0, 16, v159
	v_and_b32_e32 v3, 0xffff0000, v159
	v_mul_f32_e32 v0, v114, v0
	v_mul_f32_e32 v3, v115, v3
	v_cvt_pk_bf16_f32 v159, v0, v3
	global_store_dwordx4 v[154:155], v[156:159], off offset:256
	v_mad_i64_i32 v[154:155], s[2:3], v132, s91, v[150:151]
	v_lshl_add_u64 v[164:165], v[154:155], 0, s[76:77]
	v_lshl_add_u64 v[154:155], v[164:165], 0, v[148:149]
	v_mad_i64_i32 v[150:151], s[2:3], v2, s91, v[150:151]
	v_lshl_add_u64 v[150:151], v[150:151], 0, s[76:77]
	s_waitcnt vmcnt(14)
	v_mov_b32_e32 v154, v212
	v_mov_b32_e32 v155, v213
	v_mov_b32_e32 v156, v214
	v_mov_b32_e32 v157, v215
	v_lshlrev_b32_e32 v0, 16, v154
	v_and_b32_e32 v3, 0xffff0000, v154
	v_mul_f32_e32 v0, v84, v0
	v_mul_f32_e32 v3, v85, v3
	v_cvt_pk_bf16_f32 v158, v0, v3
	v_lshlrev_b32_e32 v0, 16, v155
	v_and_b32_e32 v3, 0xffff0000, v155
	v_mul_f32_e32 v0, v86, v0
	v_mul_f32_e32 v3, v87, v3
	v_cvt_pk_bf16_f32 v159, v0, v3
	v_lshlrev_b32_e32 v0, 16, v156
	v_and_b32_e32 v3, 0xffff0000, v156
	v_mul_f32_e32 v0, v88, v0
	v_mul_f32_e32 v3, v89, v3
	v_lshl_add_u64 v[154:155], s[8:9], 0, v[162:163]
	v_cvt_pk_bf16_f32 v160, v0, v3
	v_lshlrev_b32_e32 v0, 16, v157
	v_and_b32_e32 v3, 0xffff0000, v157
	v_lshl_add_u64 v[154:155], v[154:155], 0, v[148:149]
	v_lshl_add_u64 v[156:157], v[164:165], 0, v[152:153]
	v_mul_f32_e32 v0, v90, v0
	v_mul_f32_e32 v3, v91, v3
	v_cvt_pk_bf16_f32 v161, v0, v3
	global_store_dwordx4 v[154:155], v[158:161], off
	s_waitcnt vmcnt(13)
	v_mov_b32_e32 v156, v216
	v_mov_b32_e32 v157, v217
	v_mov_b32_e32 v158, v218
	v_mov_b32_e32 v159, v219
	v_lshlrev_b32_e32 v0, 16, v156
	v_and_b32_e32 v3, 0xffff0000, v156
	v_mul_f32_e32 v0, v116, v0
	v_mul_f32_e32 v3, v117, v3
	v_cvt_pk_bf16_f32 v156, v0, v3
	v_lshlrev_b32_e32 v0, 16, v157
	v_and_b32_e32 v3, 0xffff0000, v157
	v_mul_f32_e32 v0, v118, v0
	v_mul_f32_e32 v3, v119, v3
	v_cvt_pk_bf16_f32 v157, v0, v3
	v_lshlrev_b32_e32 v0, 16, v158
	v_and_b32_e32 v3, 0xffff0000, v158
	v_mul_f32_e32 v0, v120, v0
	v_mul_f32_e32 v3, v121, v3
	v_cvt_pk_bf16_f32 v158, v0, v3
	v_lshlrev_b32_e32 v0, 16, v159
	v_and_b32_e32 v3, 0xffff0000, v159
	v_mul_f32_e32 v0, v122, v0
	v_mul_f32_e32 v3, v123, v3
	v_cvt_pk_bf16_f32 v159, v0, v3
	global_store_dwordx4 v[154:155], v[156:159], off offset:256
	v_lshl_add_u64 v[154:155], v[150:151], 0, v[148:149]
	v_lshl_add_u64 v[150:151], v[150:151], 0, v[152:153]
	v_ashrrev_i32_e32 v3, 31, v2
	v_lshlrev_b64 v[158:159], 12, v[2:3]
	v_lshl_add_u64 v[158:159], s[8:9], 0, v[158:159]
	v_lshl_add_u64 v[148:149], v[158:159], 0, v[148:149]
	s_waitcnt vmcnt(10)
	v_mov_b32_e32 v154, v220
	v_mov_b32_e32 v155, v221
	v_mov_b32_e32 v156, v222
	v_mov_b32_e32 v157, v223
	v_mov_b32_e32 v150, v224
	v_mov_b32_e32 v151, v225
	v_mov_b32_e32 v152, v226
	v_mov_b32_e32 v153, v227
	v_lshlrev_b32_e32 v0, 16, v154
	v_and_b32_e32 v3, 0xffff0000, v154
	v_mul_f32_e32 v0, v92, v0
	v_mul_f32_e32 v3, v93, v3
	v_cvt_pk_bf16_f32 v154, v0, v3
	v_lshlrev_b32_e32 v0, 16, v155
	v_and_b32_e32 v3, 0xffff0000, v155
	v_mul_f32_e32 v0, v94, v0
	v_mul_f32_e32 v3, v95, v3
	v_cvt_pk_bf16_f32 v155, v0, v3
	v_lshlrev_b32_e32 v0, 16, v156
	v_and_b32_e32 v3, 0xffff0000, v156
	v_mul_f32_e32 v0, v96, v0
	v_mul_f32_e32 v3, v97, v3
	v_cvt_pk_bf16_f32 v156, v0, v3
	v_lshlrev_b32_e32 v0, 16, v157
	v_and_b32_e32 v3, 0xffff0000, v157
	v_mul_f32_e32 v0, v98, v0
	v_mul_f32_e32 v3, v99, v3
	v_cvt_pk_bf16_f32 v157, v0, v3
	v_lshlrev_b32_e32 v0, 16, v150
	v_and_b32_e32 v3, 0xffff0000, v150
	v_mul_f32_e32 v0, v124, v0
	v_mul_f32_e32 v3, v125, v3
	v_cvt_pk_bf16_f32 v150, v0, v3
	v_lshlrev_b32_e32 v0, 16, v151
	v_and_b32_e32 v3, 0xffff0000, v151
	v_mul_f32_e32 v0, v126, v0
	v_mul_f32_e32 v3, v127, v3
	v_cvt_pk_bf16_f32 v151, v0, v3
	v_lshlrev_b32_e32 v0, 16, v152
	v_and_b32_e32 v3, 0xffff0000, v152
	v_mul_f32_e32 v0, v128, v0
	v_mul_f32_e32 v3, v129, v3
	v_cvt_pk_bf16_f32 v152, v0, v3
	v_lshlrev_b32_e32 v0, 16, v153
	v_and_b32_e32 v3, 0xffff0000, v153
	global_store_dwordx4 v[148:149], v[154:157], off
	v_mul_f32_e32 v0, v130, v0
	v_mul_f32_e32 v3, v131, v3
	v_cvt_pk_bf16_f32 v153, v0, v3
	global_store_dwordx4 v[148:149], v[150:153], off offset:256
	s_cbranch_execnz .LBB0_907
